# LRU dir-0 MFMA block: A-fragment LDS reads four deep through dedicated register quads (same MFMA order)
# baseline (speedup 1.0000x reference)
; DI unsigned cvtpk(float lo, float hi) { unsigned r; asm volatile("v_cvt_pk_bf16_f32 %0, %1, %2" : "=v"(r) : "v"(lo), "v"(hi)); return r; }
; DI float bflo(unsigned w) { return __uint_as_float(w << 16); }
; DI float bfhi(unsigned w) { return __uint_as_float(w & 0xffff0000u); }
; DI void lru_tile(const Params& p, unsigned char* shm, int c, int nb, const LruPar par) {
;     ...
;         const int cgp = tid & 15, rg = tid >> 4, ch = nb * 128 + cgp * 8;
;         const float* cw = p.in[3]; const float* cb = p.in[4];
;         float w[4][8], bias[8];
; #pragma unroll
;         for (int tp = 0; tp < 4; ++tp) { const f32x4 a = *(const f32x4*)(cw + tp * 2048 + ch), b = *(const f32x4*)(cw + tp * 2048 + ch + 4);
;             w[tp][0] = a[0]; w[tp][1] = a[1]; w[tp][2] = a[2]; w[tp][3] = a[3]; w[tp][4] = b[0]; w[tp][5] = b[1]; w[tp][6] = b[2]; w[tp][7] = b[3]; }
;         { const f32x4 a = *(const f32x4*)(cb + ch), b = *(const f32x4*)(cb + ch + 4);
;             bias[0] = a[0]; bias[1] = a[1]; bias[2] = a[2]; bias[3] = a[3]; bias[4] = b[0]; bias[5] = b[1]; bias[6] = b[2]; bias[7] = b[3]; }
;         float xr[7][8];
; #pragma unroll
;         for (int k = 0; k < 7; ++k) { const int t = c * 128 + rg * 4 - 2 + k;
;             u32x4 v = {0u, 0u, 0u, 0u};
;             if (t >= 0 && t < S) v = *(const u32x4*)(ZU + (size_t)(nb >> 1) * S * 256 + (size_t)t * 256 + (nb & 1) * 128 + cgp * 8);
; #pragma unroll
;             for (int i = 0; i < 4; ++i) { xr[k][2 * i] = bflo(v[i]); xr[k][2 * i + 1] = bfhi(v[i]); } }
; #pragma unroll
;         for (int o = 0; o < 4; ++o) { float u8[8];
; #pragma unroll
;             for (int i = 0; i < 8; ++i) { float a = bias[i];
; #pragma unroll
;                 for (int tp = 0; tp < 4; ++tp) a += xr[o + tp][i] * w[tp][i];
;                 u8[i] = a; }
;             *(u32x4*)(UB + (rg * 4 + o) * LDU + cgp * 8) = (u32x4){cvtpk(u8[0], u8[1]), cvtpk(u8[2], u8[3]), cvtpk(u8[4], u8[5]), cvtpk(u8[6], u8[7])};
;         }
;     ...
;             for (int gt = 0; gt < 2; ++gt) bfr[s][gt] = *(const bf16x8*)(LWT + ((size_t)((d * 2 + gt) * 16 + nb) * 128 + chl) * 128 + s * 32 + q * 8);
.Llru_rows_join:
	v_and_b32_e32 v240, 0x3c0, v202
	v_lshrrev_b32_e32 v240, 2, v240
	v_and_or_b32 v240, v202, 15, v240
	v_add_u32_e32 v240, s38, v240
	v_bfe_u32 v241, v202, 4, 2
	v_lshlrev_b32_e32 v240, 8, v240
	v_lshl_add_u32 v240, v241, 4, v240
	s_add_u32 s72, s34, 0x80000
	s_addc_u32 s73, s35, 0
	global_load_dwordx4 v[208:211], v240, s[34:35]
	global_load_dwordx4 v[216:219], v240, s[34:35] offset:64
	global_load_dwordx4 v[212:215], v240, s[72:73]
	global_load_dwordx4 v[220:223], v240, s[72:73] offset:64
	global_load_dwordx4 v[224:227], v240, s[34:35] offset:128
	global_load_dwordx4 v[232:235], v240, s[34:35] offset:192
	global_load_dwordx4 v[228:231], v240, s[72:73] offset:128
	global_load_dwordx4 v[236:239], v240, s[72:73] offset:192
	v_lshlrev_b32_e32 v96, 1, v98
	v_mad_u32_u24 v96, v95, s67, v96
	v_lshlrev_b32_e32 v100, 16, v40
	v_and_b32_e32 v101, 0xffff0000, v40
	v_lshlrev_b32_e32 v102, 16, v41
	v_and_b32_e32 v103, 0xffff0000, v41
	v_lshlrev_b32_e32 v104, 16, v42
	v_and_b32_e32 v105, 0xffff0000, v42
	v_lshlrev_b32_e32 v106, 16, v43
	v_and_b32_e32 v107, 0xffff0000, v43
	v_lshlrev_b32_e32 v108, 16, v44
	v_and_b32_e32 v109, 0xffff0000, v44
	v_lshlrev_b32_e32 v110, 16, v45
	v_and_b32_e32 v111, 0xffff0000, v45
	v_lshlrev_b32_e32 v112, 16, v46
	v_and_b32_e32 v113, 0xffff0000, v46
	v_lshlrev_b32_e32 v114, 16, v47
	v_and_b32_e32 v115, 0xffff0000, v47
	v_lshlrev_b32_e32 v116, 16, v48
	v_and_b32_e32 v117, 0xffff0000, v48
	v_lshlrev_b32_e32 v118, 16, v49
	v_and_b32_e32 v119, 0xffff0000, v49
	v_lshlrev_b32_e32 v120, 16, v50
	v_and_b32_e32 v121, 0xffff0000, v50
	v_lshlrev_b32_e32 v122, 16, v51
	v_and_b32_e32 v123, 0xffff0000, v51
	v_lshlrev_b32_e32 v124, 16, v52
	v_and_b32_e32 v125, 0xffff0000, v52
	v_lshlrev_b32_e32 v126, 16, v53
	v_and_b32_e32 v127, 0xffff0000, v53
	v_lshlrev_b32_e32 v128, 16, v54
	v_and_b32_e32 v129, 0xffff0000, v54
	v_lshlrev_b32_e32 v130, 16, v55
	v_and_b32_e32 v131, 0xffff0000, v55
	v_pk_fma_f32 v[132:133], v[100:101], v[36:37], v[20:21]
	v_pk_fma_f32 v[134:135], v[102:103], v[38:39], v[22:23]
	v_pk_fma_f32 v[136:137], v[104:105], v[28:29], v[8:9]
	v_pk_fma_f32 v[138:139], v[106:107], v[30:31], v[10:11]
	v_pk_fma_f32 v[132:133], v[108:109], v[12:13], v[132:133]
	v_pk_fma_f32 v[134:135], v[110:111], v[14:15], v[134:135]
	v_pk_fma_f32 v[136:137], v[112:113], v[0:1], v[136:137]
	v_pk_fma_f32 v[138:139], v[114:115], v[2:3], v[138:139]
	v_pk_fma_f32 v[132:133], v[116:117], v[32:33], v[132:133]
	v_pk_fma_f32 v[134:135], v[118:119], v[34:35], v[134:135]
	v_pk_fma_f32 v[136:137], v[120:121], v[24:25], v[136:137]
	v_pk_fma_f32 v[138:139], v[122:123], v[26:27], v[138:139]
	v_pk_fma_f32 v[132:133], v[124:125], v[16:17], v[132:133]
	v_pk_fma_f32 v[134:135], v[126:127], v[18:19], v[134:135]
	v_pk_fma_f32 v[136:137], v[128:129], v[4:5], v[136:137]
	v_pk_fma_f32 v[138:139], v[130:131], v[6:7], v[138:139]
	v_cvt_pk_bf16_f32 v140, v132, v133
	v_cvt_pk_bf16_f32 v141, v134, v135
	v_cvt_pk_bf16_f32 v142, v136, v137
	v_cvt_pk_bf16_f32 v143, v138, v139
	ds_write_b128 v96, v[140:143]
	v_lshlrev_b32_e32 v100, 16, v56
	v_and_b32_e32 v101, 0xffff0000, v56
	v_lshlrev_b32_e32 v102, 16, v57
	v_and_b32_e32 v103, 0xffff0000, v57
	v_lshlrev_b32_e32 v104, 16, v58
	v_and_b32_e32 v105, 0xffff0000, v58
	v_lshlrev_b32_e32 v106, 16, v59
	v_and_b32_e32 v107, 0xffff0000, v59
	v_pk_fma_f32 v[132:133], v[108:109], v[36:37], v[20:21]
	v_pk_fma_f32 v[134:135], v[110:111], v[38:39], v[22:23]
	v_pk_fma_f32 v[136:137], v[112:113], v[28:29], v[8:9]
	v_pk_fma_f32 v[138:139], v[114:115], v[30:31], v[10:11]
	v_pk_fma_f32 v[132:133], v[116:117], v[12:13], v[132:133]
	v_pk_fma_f32 v[134:135], v[118:119], v[14:15], v[134:135]
	v_pk_fma_f32 v[136:137], v[120:121], v[0:1], v[136:137]
	v_pk_fma_f32 v[138:139], v[122:123], v[2:3], v[138:139]
	v_pk_fma_f32 v[132:133], v[124:125], v[32:33], v[132:133]
	v_pk_fma_f32 v[134:135], v[126:127], v[34:35], v[134:135]
	v_pk_fma_f32 v[136:137], v[128:129], v[24:25], v[136:137]
	v_pk_fma_f32 v[138:139], v[130:131], v[26:27], v[138:139]
	v_pk_fma_f32 v[132:133], v[100:101], v[16:17], v[132:133]
	v_pk_fma_f32 v[134:135], v[102:103], v[18:19], v[134:135]
	v_pk_fma_f32 v[136:137], v[104:105], v[4:5], v[136:137]
	v_pk_fma_f32 v[138:139], v[106:107], v[6:7], v[138:139]
	v_cvt_pk_bf16_f32 v140, v132, v133
	v_cvt_pk_bf16_f32 v141, v134, v135
	v_cvt_pk_bf16_f32 v142, v136, v137
	v_cvt_pk_bf16_f32 v143, v138, v139
	ds_write_b128 v96, v[140:143] offset:272
	v_lshlrev_b32_e32 v108, 16, v60
	v_and_b32_e32 v109, 0xffff0000, v60
	v_lshlrev_b32_e32 v110, 16, v61
	v_and_b32_e32 v111, 0xffff0000, v61
	v_lshlrev_b32_e32 v112, 16, v62
	v_and_b32_e32 v113, 0xffff0000, v62
	v_lshlrev_b32_e32 v114, 16, v63
	v_and_b32_e32 v115, 0xffff0000, v63
	v_pk_fma_f32 v[132:133], v[116:117], v[36:37], v[20:21]
	v_pk_fma_f32 v[134:135], v[118:119], v[38:39], v[22:23]
	v_pk_fma_f32 v[136:137], v[120:121], v[28:29], v[8:9]
	v_pk_fma_f32 v[138:139], v[122:123], v[30:31], v[10:11]
	v_pk_fma_f32 v[132:133], v[124:125], v[12:13], v[132:133]
	v_pk_fma_f32 v[134:135], v[126:127], v[14:15], v[134:135]
	v_pk_fma_f32 v[136:137], v[128:129], v[0:1], v[136:137]
	v_pk_fma_f32 v[138:139], v[130:131], v[2:3], v[138:139]
	v_pk_fma_f32 v[132:133], v[100:101], v[32:33], v[132:133]
	v_pk_fma_f32 v[134:135], v[102:103], v[34:35], v[134:135]
	v_pk_fma_f32 v[136:137], v[104:105], v[24:25], v[136:137]
	v_pk_fma_f32 v[138:139], v[106:107], v[26:27], v[138:139]
	v_pk_fma_f32 v[132:133], v[108:109], v[16:17], v[132:133]
	v_pk_fma_f32 v[134:135], v[110:111], v[18:19], v[134:135]
	v_pk_fma_f32 v[136:137], v[112:113], v[4:5], v[136:137]
	v_pk_fma_f32 v[138:139], v[114:115], v[6:7], v[138:139]
; DI unsigned cvtpk(float lo, float hi) { unsigned r; asm volatile("v_cvt_pk_bf16_f32 %0, %1, %2" : "=v"(r) : "v"(lo), "v"(hi)); return r; }
; DI void lru_tile(const Params& p, unsigned char* shm, int c, int nb, const LruPar par) {
;     ...
;         for (int o = 0; o < 4; ++o) { float u8[8];
; #pragma unroll
;             for (int i = 0; i < 8; ++i) { float a = bias[i];
; #pragma unroll
;                 for (int tp = 0; tp < 4; ++tp) a += xr[o + tp][i] * w[tp][i];
;                 u8[i] = a; }
;             *(u32x4*)(UB + (rg * 4 + o) * LDU + cgp * 8) = (u32x4){cvtpk(u8[0], u8[1]), cvtpk(u8[2], u8[3]), cvtpk(u8[4], u8[5]), cvtpk(u8[6], u8[7])};
;         }
;     ...
;         for (int s = 0; s < 4; ++s)
; #pragma unroll
;             for (int gt = 0; gt < 2; ++gt) bfr[s][gt] = *(const bf16x8*)(LWT + ((size_t)((d * 2 + gt) * 16 + nb) * 128 + chl) * 128 + s * 32 + q * 8);
; #pragma unroll
;         for (int s = 0; s < 4; ++s) {
; #pragma unroll
;             for (int rt = 0; rt < 8; ++rt) {
;                 const bf16x8 af = *(const bf16x8*)(UB + (rt * 16 + col) * LDU + s * 32 + q * 8);
; #pragma unroll
;                 for (int gt = 0; gt < 2; ++gt) acc[gt][rt] = __builtin_amdgcn_mfma_f32_16x16x32_bf16(af, bfr[s][gt], acc[gt][rt], 0, 0, 0);
;             }
;             __builtin_amdgcn_sched_barrier(0);
;         }
	v_cvt_pk_bf16_f32 v140, v132, v133
	v_cvt_pk_bf16_f32 v141, v134, v135
	v_cvt_pk_bf16_f32 v142, v136, v137
	v_cvt_pk_bf16_f32 v143, v138, v139
	ds_write_b128 v96, v[140:143] offset:544
	v_lshlrev_b32_e32 v116, 16, v64
	v_and_b32_e32 v117, 0xffff0000, v64
	v_lshlrev_b32_e32 v118, 16, v65
	v_and_b32_e32 v119, 0xffff0000, v65
	v_lshlrev_b32_e32 v120, 16, v66
	v_and_b32_e32 v121, 0xffff0000, v66
	v_lshlrev_b32_e32 v122, 16, v67
	v_and_b32_e32 v123, 0xffff0000, v67
	v_pk_fma_f32 v[132:133], v[124:125], v[36:37], v[20:21]
	v_pk_fma_f32 v[134:135], v[126:127], v[38:39], v[22:23]
	v_pk_fma_f32 v[136:137], v[128:129], v[28:29], v[8:9]
	v_pk_fma_f32 v[138:139], v[130:131], v[30:31], v[10:11]
	v_pk_fma_f32 v[132:133], v[100:101], v[12:13], v[132:133]
	v_pk_fma_f32 v[134:135], v[102:103], v[14:15], v[134:135]
	v_pk_fma_f32 v[136:137], v[104:105], v[0:1], v[136:137]
	v_pk_fma_f32 v[138:139], v[106:107], v[2:3], v[138:139]
	v_pk_fma_f32 v[132:133], v[108:109], v[32:33], v[132:133]
	v_pk_fma_f32 v[134:135], v[110:111], v[34:35], v[134:135]
	v_pk_fma_f32 v[136:137], v[112:113], v[24:25], v[136:137]
	v_pk_fma_f32 v[138:139], v[114:115], v[26:27], v[138:139]
	v_pk_fma_f32 v[132:133], v[116:117], v[16:17], v[132:133]
	v_pk_fma_f32 v[134:135], v[118:119], v[18:19], v[134:135]
	v_pk_fma_f32 v[136:137], v[120:121], v[4:5], v[136:137]
	v_pk_fma_f32 v[138:139], v[122:123], v[6:7], v[138:139]
	v_cvt_pk_bf16_f32 v140, v132, v133
	v_cvt_pk_bf16_f32 v141, v134, v135
	v_cvt_pk_bf16_f32 v142, v136, v137
	v_cvt_pk_bf16_f32 v143, v138, v139
	ds_write_b128 v96, v[140:143] offset:816
	s_ashr_i32 s4, s6, 6
	v_and_b32_e32 v164, 15, v75
	v_lshl_or_b32 v48, s4, 4, v164
	s_lshl_b32 s4, s4, 12
	s_ashr_i32 s59, s58, 31
	s_add_i32 s8, s4, 0
	s_lshl_b64 s[4:5], s[58:59], 14
	v_bfe_u32 v99, v75, 4, 2
	v_ashrrev_i32_e32 v49, 31, v48
	s_add_u32 s4, s37, s4
	s_addc_u32 s5, s41, s5
	v_lshlrev_b32_e32 v68, 4, v99
	v_lshl_add_u64 v[160:161], s[34:35], 0, v[68:69]
	v_add_u32_e32 v165, 0, v68
	s_waitcnt lgkmcnt(0)
	s_barrier
	v_mad_u32_u24 v68, v164, s67, v165
	v_lshl_add_u64 v[96:97], v[160:161], 0, v[8:9]
	ds_read_b128 v[4:7], v68
	ds_read_b128 v[12:15], v68 offset:4352
	ds_read_b128 v[32:35], v68 offset:8704
	ds_read_b128 v[36:39], v68 offset:13056
	ds_read_b128 v[50:53], v68 offset:17408
	ds_read_b128 v[54:57], v68 offset:21760
	ds_read_b128 v[58:61], v68 offset:26112
	ds_read_b128 v[116:119], v68 offset:30464
	s_waitcnt vmcnt(7) lgkmcnt(7)
	v_mfma_f32_16x16x32_bf16 v[16:19], v[4:7], v[208:211], 0
	v_cmp_eq_u32_e64 s[10:11], 0, v99
	s_waitcnt lgkmcnt(6)
	v_mfma_f32_16x16x32_bf16 v[28:31], v[12:15], v[208:211], 0
	s_waitcnt lgkmcnt(5)
	v_mfma_f32_16x16x32_bf16 v[40:43], v[32:35], v[208:211], 0
	s_waitcnt lgkmcnt(4)
	v_mfma_f32_16x16x32_bf16 v[44:47], v[36:39], v[208:211], 0
	s_waitcnt lgkmcnt(3)
	v_mfma_f32_16x16x32_bf16 v[62:65], v[50:53], v[208:211], 0
	s_waitcnt vmcnt(5)
	v_mfma_f32_16x16x32_bf16 v[50:53], v[50:53], v[212:215], 0
	s_waitcnt lgkmcnt(2)
	v_mfma_f32_16x16x32_bf16 v[100:103], v[54:57], v[208:211], 0
	v_mfma_f32_16x16x32_bf16 v[104:107], v[54:57], v[212:215], 0
	v_lshl_add_u32 v55, v164, 3, s8
	v_add_u32_e32 v54, s38, v48
	s_waitcnt lgkmcnt(1)
	v_mfma_f32_16x16x32_bf16 v[120:123], v[58:61], v[208:211], 0
	v_mfma_f32_16x16x32_bf16 v[132:135], v[58:61], v[212:215], 0
	v_add_u32_e32 v59, 0x19800, v55
	v_ashrrev_i32_e32 v55, 31, v54
	v_lshlrev_b32_e32 v58, 1, v48
	s_waitcnt lgkmcnt(0)
	ds_read_b128 v[144:147], v68 offset:64
	ds_read_b128 v[148:151], v68 offset:4416
	ds_read_b128 v[152:155], v68 offset:8768
	ds_read_b128 v[156:159], v68 offset:13120
	v_mfma_f32_16x16x32_bf16 v[0:3], v[116:119], v[208:211], 0
	v_lshl_add_u32 v61, v99, 7, v59
	v_lshl_add_u64 v[56:57], v[54:55], 3, s[4:5]
	v_mfma_f32_16x16x32_bf16 v[4:7], v[4:7], v[212:215], 0
	v_mfma_f32_16x16x32_bf16 v[12:15], v[12:15], v[212:215], 0
	v_mfma_f32_16x16x32_bf16 v[32:35], v[32:35], v[212:215], 0
	v_mfma_f32_16x16x32_bf16 v[36:39], v[36:39], v[212:215], 0
	v_mfma_f32_16x16x32_bf16 v[20:23], v[116:119], v[212:215], 0
	s_waitcnt lgkmcnt(3)
	v_mfma_f32_16x16x32_bf16 v[16:19], v[144:147], v[216:219], v[16:19]
	s_waitcnt vmcnt(4)
	v_mfma_f32_16x16x32_bf16 v[4:7], v[144:147], v[220:223], v[4:7]
	ds_read_b128 v[144:147], v68 offset:17472
	s_waitcnt lgkmcnt(3)
	v_mfma_f32_16x16x32_bf16 v[28:31], v[148:151], v[216:219], v[28:31]
	v_mfma_f32_16x16x32_bf16 v[12:15], v[148:151], v[220:223], v[12:15]
	ds_read_b128 v[148:151], v68 offset:21824
	s_waitcnt lgkmcnt(3)
	v_mfma_f32_16x16x32_bf16 v[40:43], v[152:155], v[216:219], v[40:43]
	v_mfma_f32_16x16x32_bf16 v[32:35], v[152:155], v[220:223], v[32:35]
	ds_read_b128 v[152:155], v68 offset:26176
	s_waitcnt lgkmcnt(3)
	v_mfma_f32_16x16x32_bf16 v[44:47], v[156:159], v[216:219], v[44:47]
	v_mfma_f32_16x16x32_bf16 v[36:39], v[156:159], v[220:223], v[36:39]
	ds_read_b128 v[156:159], v68 offset:30528
	s_waitcnt lgkmcnt(3)
	v_mfma_f32_16x16x32_bf16 v[62:65], v[144:147], v[216:219], v[62:65]
	v_mfma_f32_16x16x32_bf16 v[50:53], v[144:147], v[220:223], v[50:53]
	ds_read_b128 v[144:147], v68 offset:128
	s_waitcnt lgkmcnt(3)
	v_mfma_f32_16x16x32_bf16 v[100:103], v[148:151], v[216:219], v[100:103]
	v_mfma_f32_16x16x32_bf16 v[104:107], v[148:151], v[220:223], v[104:107]
	ds_read_b128 v[148:151], v68 offset:4480
	s_waitcnt lgkmcnt(3)
	v_mfma_f32_16x16x32_bf16 v[120:123], v[152:155], v[216:219], v[120:123]
	v_mfma_f32_16x16x32_bf16 v[116:119], v[152:155], v[220:223], v[132:135]
	ds_read_b128 v[152:155], v68 offset:8832
	s_waitcnt lgkmcnt(3)
	v_mfma_f32_16x16x32_bf16 v[0:3], v[156:159], v[216:219], v[0:3]
	v_mfma_f32_16x16x32_bf16 v[8:11], v[156:159], v[220:223], v[20:23]
	ds_read_b128 v[156:159], v68 offset:13184
	s_waitcnt lgkmcnt(3)
; DI float bf2f(unsigned short b) { return __uint_as_float(((unsigned)b) << 16); }
; DI float ex2(float x) { return __builtin_amdgcn_exp2f(x); }
; DI float rcpf_(float x) { return __builtin_amdgcn_rcpf(x); }
; DI void lru_tile(const Params& p, unsigned char* shm, int c, int nb, const LruPar par) {
;     ...
;         for (int s = 0; s < 4; ++s)
; #pragma unroll
;             for (int gt = 0; gt < 2; ++gt) bfr[s][gt] = *(const bf16x8*)(LWT + ((size_t)((d * 2 + gt) * 16 + nb) * 128 + chl) * 128 + s * 32 + q * 8);
; #pragma unroll
;         for (int s = 0; s < 4; ++s) {
; #pragma unroll
;             for (int rt = 0; rt < 8; ++rt) {
;                 const bf16x8 af = *(const bf16x8*)(UB + (rt * 16 + col) * LDU + s * 32 + q * 8);
; #pragma unroll
;                 for (int gt = 0; gt < 2; ++gt) acc[gt][rt] = __builtin_amdgcn_mfma_f32_16x16x32_bf16(af, bfr[s][gt], acc[gt][rt], 0, 0, 0);
;             }
;             __builtin_amdgcn_sched_barrier(0);
;         }
;         const f32x2 nl2 = {-LOG2E, -LOG2E}, nbr2 = {par.nbr[d], par.nbr[d]}, nbi2 = {par.nbi[d], par.nbi[d]}, cd2 = {par.cdec[d], par.cdec[d]}, one2 = {1.f, 1.f};
;         float hl[8][4], pc[8][4];
; #pragma unroll
;         for (int rt = 0; rt < 8; ++rt) {
;             float av[4], bv[4];
; #pragma unroll
;             for (int jp = 0; jp < 2; ++jp) {
;                 const f32x2 xr = {acc[0][rt][2 * jp], acc[0][rt][2 * jp + 1]}, xi = {acc[1][rt][2 * jp], acc[1][rt][2 * jp + 1]};
;                 f32x2 er = xr * nl2 + nbr2, ei = xi * nl2 + nbi2;
;                 er = (f32x2){ex2(er[0]), ex2(er[1])} + one2; ei = (f32x2){ex2(ei[0]), ex2(ei[1])} + one2;
;                 const f32x2 r = {rcpf_(er[0]), rcpf_(er[1])}, ig = {rcpf_(ei[0]), rcpf_(ei[1])};
;                 const f32x2 la = r * cd2;
;                 const f32x2 a = {ex2(la[0]), ex2(la[1])};
;                 const f32x2 om = one2 - a * a;
;                 const f32x2 sc = {__builtin_amdgcn_sqrtf(om[0]), __builtin_amdgcn_sqrtf(om[1])};
;                 const f32x2 u2 = {bf2f(UB[(rt * 16 + 4 * q + 2 * jp) * LDU + chl]), bf2f(UB[(rt * 16 + 4 * q + 2 * jp + 1) * LDU + chl])};
;                 const f32x2 b2 = sc * ig * u2;
;                 av[2 * jp] = a[0]; av[2 * jp + 1] = a[1]; bv[2 * jp] = b2[0]; bv[2 * jp + 1] = b2[1];
;             }
	s_waitcnt vmcnt(3)
	v_mfma_f32_16x16x32_bf16 v[16:19], v[144:147], v[224:227], v[16:19]
	s_waitcnt vmcnt(1)
	v_mfma_f32_16x16x32_bf16 v[4:7], v[144:147], v[228:231], v[4:7]
	ds_read_b128 v[144:147], v68 offset:17536
	s_waitcnt lgkmcnt(3)
	v_mfma_f32_16x16x32_bf16 v[20:23], v[148:151], v[224:227], v[28:31]
	v_mfma_f32_16x16x32_bf16 v[12:15], v[148:151], v[228:231], v[12:15]
	ds_read_b128 v[148:151], v68 offset:21888
	s_waitcnt lgkmcnt(3)
	v_mfma_f32_16x16x32_bf16 v[40:43], v[152:155], v[224:227], v[40:43]
	v_mfma_f32_16x16x32_bf16 v[24:27], v[152:155], v[228:231], v[32:35]
	ds_read_b128 v[152:155], v68 offset:26240
	s_waitcnt lgkmcnt(3)
	v_mfma_f32_16x16x32_bf16 v[32:35], v[156:159], v[224:227], v[44:47]
	v_mfma_f32_16x16x32_bf16 v[28:31], v[156:159], v[228:231], v[36:39]
	ds_read_b128 v[156:159], v68 offset:30592
	s_waitcnt lgkmcnt(3)
	v_mfma_f32_16x16x32_bf16 v[62:65], v[144:147], v[224:227], v[62:65]
	v_mfma_f32_16x16x32_bf16 v[50:53], v[144:147], v[228:231], v[50:53]
	ds_read_b128 v[144:147], v68 offset:192
	s_waitcnt lgkmcnt(3)
	v_mfma_f32_16x16x32_bf16 v[100:103], v[148:151], v[224:227], v[100:103]
	v_mfma_f32_16x16x32_bf16 v[104:107], v[148:151], v[228:231], v[104:107]
	ds_read_b128 v[148:151], v68 offset:4544
	s_waitcnt lgkmcnt(3)
	v_mfma_f32_16x16x32_bf16 v[120:123], v[152:155], v[224:227], v[120:123]
	v_mfma_f32_16x16x32_bf16 v[116:119], v[152:155], v[228:231], v[116:119]
	ds_read_b128 v[152:155], v68 offset:8896
	s_waitcnt lgkmcnt(3)
	v_mfma_f32_16x16x32_bf16 v[0:3], v[156:159], v[224:227], v[0:3]
	v_mfma_f32_16x16x32_bf16 v[108:111], v[156:159], v[228:231], v[8:11]
	ds_read_b128 v[156:159], v68 offset:13248
	s_waitcnt lgkmcnt(3)
	v_mfma_f32_16x16x32_bf16 v[124:127], v[144:147], v[232:235], v[16:19]
	s_waitcnt vmcnt(0)
	v_mfma_f32_16x16x32_bf16 v[132:135], v[144:147], v[236:239], v[4:7]
	ds_read_b128 v[144:147], v68 offset:17600
	s_waitcnt lgkmcnt(3)
	v_mfma_f32_16x16x32_bf16 v[136:139], v[148:151], v[232:235], v[20:23]
	v_mfma_f32_16x16x32_bf16 v[140:143], v[148:151], v[236:239], v[12:15]
	ds_read_b128 v[148:151], v68 offset:21952
	s_waitcnt lgkmcnt(3)
	v_mfma_f32_16x16x32_bf16 v[44:47], v[152:155], v[232:235], v[40:43]
	v_mfma_f32_16x16x32_bf16 v[40:43], v[152:155], v[236:239], v[24:27]
	ds_read_b128 v[152:155], v68 offset:26304
	s_waitcnt lgkmcnt(3)
	v_mfma_f32_16x16x32_bf16 v[36:39], v[156:159], v[232:235], v[32:35]
	v_mfma_f32_16x16x32_bf16 v[32:35], v[156:159], v[236:239], v[28:31]
	ds_read_b128 v[156:159], v68 offset:30656
	s_waitcnt lgkmcnt(3)
	v_mfma_f32_16x16x32_bf16 v[28:31], v[144:147], v[232:235], v[62:65]
	v_mfma_f32_16x16x32_bf16 v[24:27], v[144:147], v[236:239], v[50:53]
	s_waitcnt lgkmcnt(2)
	v_mfma_f32_16x16x32_bf16 v[20:23], v[148:151], v[232:235], v[100:103]
	v_mfma_f32_16x16x32_bf16 v[16:19], v[148:151], v[236:239], v[104:107]
	s_waitcnt lgkmcnt(1)
	v_mfma_f32_16x16x32_bf16 v[12:15], v[152:155], v[232:235], v[120:123]
	v_mfma_f32_16x16x32_bf16 v[8:11], v[152:155], v[236:239], v[116:119]
	s_waitcnt lgkmcnt(0)
	v_mfma_f32_16x16x32_bf16 v[4:7], v[156:159], v[232:235], v[0:3]
	v_mfma_f32_16x16x32_bf16 v[0:3], v[156:159], v[236:239], v[108:111]
	s_add_u32 s74, s34, 0x100000
	s_addc_u32 s75, s35, 0
	s_add_u32 s76, s34, 0x180000
	s_addc_u32 s77, s35, 0
	global_load_dwordx4 v[208:211], v240, s[74:75]
	global_load_dwordx4 v[216:219], v240, s[74:75] offset:64
	global_load_dwordx4 v[212:215], v240, s[76:77]
	global_load_dwordx4 v[220:223], v240, s[76:77] offset:64
	global_load_dwordx4 v[224:227], v240, s[74:75] offset:128
	global_load_dwordx4 v[228:231], v240, s[74:75] offset:192
	global_load_dwordx4 v[232:235], v240, s[76:77] offset:128
	global_load_dwordx4 v[236:239], v240, s[76:77] offset:192
	v_fma_f32 v52, -v126, s50, v82
	v_fma_f32 v53, -v127, s50, v82
	v_pk_fma_f32 v[54:55], v[134:135], s[50:51], v[86:87] op_sel_hi:[1,0,0] neg_lo:[1,0,0] neg_hi:[1,0,0]
	v_exp_f32_e32 v52, v52
	v_exp_f32_e32 v53, v53
	v_pk_fma_f32 v[50:51], v[124:125], s[50:51], v[82:83] op_sel_hi:[1,0,0] neg_lo:[1,0,0] neg_hi:[1,0,0]
	v_exp_f32_e32 v54, v54
	v_exp_f32_e32 v55, v55
	v_pk_add_f32 v[52:53], v[52:53], 1.0 op_sel_hi:[1,0]
	v_exp_f32_e32 v50, v50
	v_rcp_f32_e32 v52, v52
	v_rcp_f32_e32 v53, v53
	v_exp_f32_e32 v51, v51
	v_mul_u32_u24_e32 v95, 0x220, v99
	v_lshlrev_b32_e32 v60, 1, v95
	v_pk_mul_f32 v[52:53], v[92:93], v[52:53] op_sel_hi:[0,1]
	v_exp_f32_e32 v62, v52
	v_exp_f32_e32 v63, v53
	v_pk_add_f32 v[52:53], v[54:55], 1.0 op_sel_hi:[1,0]
	v_pk_add_f32 v[50:51], v[50:51], 1.0 op_sel_hi:[1,0]
	v_rcp_f32_e32 v52, v52
	v_pk_fma_f32 v[54:55], v[62:63], v[62:63], 1.0 op_sel_hi:[1,1,0] neg_lo:[1,0,0] neg_hi:[1,0,0]
	v_rcp_f32_e32 v53, v53
	v_sqrt_f32_e32 v54, v54
	v_sqrt_f32_e32 v55, v55
	v_rcp_f32_e32 v50, v50
	v_rcp_f32_e32 v51, v51
	v_add3_u32 v68, 0, v58, v60
	v_pk_mul_f32 v[52:53], v[52:53], v[54:55]
	v_pk_fma_f32 v[54:55], v[132:133], s[50:51], v[86:87] op_sel_hi:[1,0,0] neg_lo:[1,0,0] neg_hi:[1,0,0]
	v_pk_mul_f32 v[50:51], v[92:93], v[50:51] op_sel_hi:[0,1]
	v_exp_f32_e32 v54, v54
	v_exp_f32_e32 v55, v55
	v_exp_f32_e32 v50, v50
	v_exp_f32_e32 v51, v51
	v_add3_u32 v97, 0, v60, v58
	ds_read_u16 v58, v68 offset:544
	ds_read_u16 v60, v97 offset:816
	v_pk_add_f32 v[54:55], v[54:55], 1.0 op_sel_hi:[1,0]
	ds_read_u16 v96, v97 offset:272
	ds_read_u16 v98, v68
	v_rcp_f32_e32 v64, v54
	v_rcp_f32_e32 v65, v55
	v_pk_fma_f32 v[54:55], v[50:51], v[50:51], 1.0 op_sel_hi:[1,1,0] neg_lo:[1,0,0] neg_hi:[1,0,0]
	s_nop 0
	v_sqrt_f32_e32 v66, v54
	v_sqrt_f32_e32 v67, v55
	s_waitcnt lgkmcnt(3)
	v_lshlrev_b32_e32 v54, 16, v58
	s_waitcnt lgkmcnt(2)
	v_lshlrev_b32_e32 v55, 16, v60
	v_pk_mul_f32 v[54:55], v[52:53], v[54:55]
	v_pk_mul_f32 v[52:53], v[64:65], v[66:67]
	s_waitcnt lgkmcnt(0)
; DI float bf2f(unsigned short b) { return __uint_as_float(((unsigned)b) << 16); }
; DI float ex2(float x) { return __builtin_amdgcn_exp2f(x); }
; DI float rcpf_(float x) { return __builtin_amdgcn_rcpf(x); }
; DI void lru_tile(const Params& p, unsigned char* shm, int c, int nb, const LruPar par) {
;     ...
;         for (int rt = 0; rt < 8; ++rt) {
;             float av[4], bv[4];
; #pragma unroll
;             for (int jp = 0; jp < 2; ++jp) {
;                 const f32x2 xr = {acc[0][rt][2 * jp], acc[0][rt][2 * jp + 1]}, xi = {acc[1][rt][2 * jp], acc[1][rt][2 * jp + 1]};
;                 f32x2 er = xr * nl2 + nbr2, ei = xi * nl2 + nbi2;
;                 er = (f32x2){ex2(er[0]), ex2(er[1])} + one2; ei = (f32x2){ex2(ei[0]), ex2(ei[1])} + one2;
;                 const f32x2 r = {rcpf_(er[0]), rcpf_(er[1])}, ig = {rcpf_(ei[0]), rcpf_(ei[1])};
;                 const f32x2 la = r * cd2;
;                 const f32x2 a = {ex2(la[0]), ex2(la[1])};
;                 const f32x2 om = one2 - a * a;
;                 const f32x2 sc = {__builtin_amdgcn_sqrtf(om[0]), __builtin_amdgcn_sqrtf(om[1])};
;                 const f32x2 u2 = {bf2f(UB[(rt * 16 + 4 * q + 2 * jp) * LDU + chl]), bf2f(UB[(rt * 16 + 4 * q + 2 * jp + 1) * LDU + chl])};
;                 const f32x2 b2 = sc * ig * u2;
;                 av[2 * jp] = a[0]; av[2 * jp + 1] = a[1]; bv[2 * jp] = b2[0]; bv[2 * jp + 1] = b2[1];
;             }
;             float h = 0.f, P = 1.f;
;             if (d == 0) {
; #pragma unroll
;                 for (int j = 0; j < 4; ++j) { h = fmaf(av[j], h, bv[j]); P *= av[j]; hl[rt][j] = h; pc[rt][j] = P; }
;             } else {
; #pragma unroll
;                 for (int j = 3; j >= 0; --j) { h = fmaf(av[j], h, bv[j]); P *= av[j]; hl[rt][j] = h; pc[rt][j] = P; }
;             }
;             AG[(rt * 4 + q) * 16 + col] = (f32x2){P, h};
;             __builtin_amdgcn_sched_barrier(0);
;         }
	v_lshlrev_b32_e32 v64, 16, v98
	v_lshlrev_b32_e32 v65, 16, v96
	v_pk_mul_f32 v[52:53], v[52:53], v[64:65]
	s_nop 0
	v_fma_f32 v52, 0, v50, v52
	v_fmac_f32_e32 v53, v51, v52
	v_mul_f32_e32 v51, v50, v51
	v_fma_f32 v58, v62, v53, v54
	v_mul_f32_e32 v60, v62, v51
	v_fmac_f32_e32 v55, v63, v58
	v_mul_f32_e32 v54, v63, v60
	ds_write_b64 v61, v[54:55]
	v_pk_fma_f32 v[64:65], v[138:139], s[50:51], v[82:83] op_sel_hi:[1,0,0] neg_lo:[1,0,0] neg_hi:[1,0,0]
	v_pk_fma_f32 v[66:67], v[142:143], s[50:51], v[86:87] op_sel_hi:[1,0,0] neg_lo:[1,0,0] neg_hi:[1,0,0]
	v_exp_f32_e32 v64, v64
	v_exp_f32_e32 v65, v65
	v_pk_fma_f32 v[62:63], v[136:137], s[50:51], v[82:83] op_sel_hi:[1,0,0] neg_lo:[1,0,0] neg_hi:[1,0,0]
	v_exp_f32_e32 v66, v66
	v_exp_f32_e32 v67, v67
	v_pk_add_f32 v[64:65], v[64:65], 1.0 op_sel_hi:[1,0]
	v_exp_f32_e32 v62, v62
	v_rcp_f32_e32 v64, v64
	v_rcp_f32_e32 v65, v65
	v_exp_f32_e32 v63, v63
	ds_read_u16 v96, v68 offset:4896
	ds_read_u16 v98, v97 offset:5168
	ds_read_u16 v106, v97 offset:4624
	ds_read_u16 v107, v68 offset:4352
	v_pk_mul_f32 v[64:65], v[92:93], v[64:65] op_sel_hi:[0,1]
	v_exp_f32_e32 v100, v64
	v_exp_f32_e32 v101, v65
	v_pk_add_f32 v[64:65], v[66:67], 1.0 op_sel_hi:[1,0]
	v_pk_add_f32 v[62:63], v[62:63], 1.0 op_sel_hi:[1,0]
	v_rcp_f32_e32 v64, v64
	v_pk_fma_f32 v[66:67], v[100:101], v[100:101], 1.0 op_sel_hi:[1,1,0] neg_lo:[1,0,0] neg_hi:[1,0,0]
	v_rcp_f32_e32 v65, v65
	v_sqrt_f32_e32 v66, v66
	v_sqrt_f32_e32 v67, v67
	v_rcp_f32_e32 v62, v62
	v_rcp_f32_e32 v63, v63
	v_pk_mul_f32 v[64:65], v[64:65], v[66:67]
	v_pk_fma_f32 v[66:67], v[140:141], s[50:51], v[86:87] op_sel_hi:[1,0,0] neg_lo:[1,0,0] neg_hi:[1,0,0]
	v_pk_mul_f32 v[62:63], v[92:93], v[62:63] op_sel_hi:[0,1]
	v_exp_f32_e32 v66, v66
	v_exp_f32_e32 v67, v67
	v_exp_f32_e32 v62, v62
	v_exp_f32_e32 v63, v63
	v_pk_add_f32 v[66:67], v[66:67], 1.0 op_sel_hi:[1,0]
	s_nop 0
	v_rcp_f32_e32 v102, v66
	v_rcp_f32_e32 v103, v67
	v_pk_fma_f32 v[66:67], v[62:63], v[62:63], 1.0 op_sel_hi:[1,1,0] neg_lo:[1,0,0] neg_hi:[1,0,0]
	s_nop 0
	v_sqrt_f32_e32 v104, v66
	v_sqrt_f32_e32 v105, v67
	s_waitcnt lgkmcnt(3)
	v_lshlrev_b32_e32 v66, 16, v96
	s_waitcnt lgkmcnt(2)
	v_lshlrev_b32_e32 v67, 16, v98
	v_pk_mul_f32 v[66:67], v[64:65], v[66:67]
	v_pk_mul_f32 v[64:65], v[102:103], v[104:105]
	s_waitcnt lgkmcnt(0)
	v_lshlrev_b32_e32 v102, 16, v107
	v_lshlrev_b32_e32 v103, 16, v106
	v_pk_mul_f32 v[64:65], v[64:65], v[102:103]
	s_nop 0
	v_fma_f32 v64, 0, v62, v64
	v_fmac_f32_e32 v65, v63, v64
	v_mul_f32_e32 v63, v62, v63
	v_fma_f32 v96, v100, v65, v66
	v_mul_f32_e32 v98, v100, v63
	v_fmac_f32_e32 v67, v101, v96
	v_mul_f32_e32 v66, v101, v98
	ds_write_b64 v61, v[66:67] offset:512
	v_pk_fma_f32 v[46:47], v[46:47], s[50:51], v[82:83] op_sel_hi:[1,0,0] neg_lo:[1,0,0] neg_hi:[1,0,0]
	v_pk_fma_f32 v[44:45], v[44:45], s[50:51], v[82:83] op_sel_hi:[1,0,0] neg_lo:[1,0,0] neg_hi:[1,0,0]
	v_exp_f32_e32 v46, v46
	v_exp_f32_e32 v47, v47
	v_exp_f32_e32 v44, v44
	v_exp_f32_e32 v45, v45
	v_pk_fma_f32 v[42:43], v[42:43], s[50:51], v[86:87] op_sel_hi:[1,0,0] neg_lo:[1,0,0] neg_hi:[1,0,0]
	v_pk_add_f32 v[46:47], v[46:47], 1.0 op_sel_hi:[1,0]
	v_exp_f32_e32 v42, v42
	v_rcp_f32_e32 v46, v46
	v_rcp_f32_e32 v47, v47
	v_pk_add_f32 v[44:45], v[44:45], 1.0 op_sel_hi:[1,0]
	v_exp_f32_e32 v43, v43
	v_rcp_f32_e32 v44, v44
	v_pk_mul_f32 v[46:47], v[92:93], v[46:47] op_sel_hi:[0,1]
	v_exp_f32_e32 v46, v46
	v_exp_f32_e32 v47, v47
	v_rcp_f32_e32 v45, v45
	v_pk_add_f32 v[42:43], v[42:43], 1.0 op_sel_hi:[1,0]
	v_pk_fma_f32 v[40:41], v[40:41], s[50:51], v[86:87] op_sel_hi:[1,0,0] neg_lo:[1,0,0] neg_hi:[1,0,0]
	v_pk_fma_f32 v[100:101], v[46:47], v[46:47], 1.0 op_sel_hi:[1,1,0] neg_lo:[1,0,0] neg_hi:[1,0,0]
	v_rcp_f32_e32 v42, v42
	v_rcp_f32_e32 v43, v43
	v_sqrt_f32_e32 v102, v100
	v_sqrt_f32_e32 v103, v101
	v_pk_mul_f32 v[44:45], v[92:93], v[44:45] op_sel_hi:[0,1]
	v_exp_f32_e32 v100, v44
	v_exp_f32_e32 v40, v40
	v_exp_f32_e32 v41, v41
	v_exp_f32_e32 v101, v45
	v_pk_mul_f32 v[42:43], v[42:43], v[102:103]
	ds_read_u16 v102, v68 offset:9248
	ds_read_u16 v103, v97 offset:9520
	v_pk_add_f32 v[40:41], v[40:41], 1.0 op_sel_hi:[1,0]
	v_pk_fma_f32 v[44:45], v[100:101], v[100:101], 1.0 op_sel_hi:[1,1,0] neg_lo:[1,0,0] neg_hi:[1,0,0]
	ds_read_u16 v106, v97 offset:8976
	ds_read_u16 v107, v68 offset:8704
	v_rcp_f32_e32 v40, v40
	v_rcp_f32_e32 v41, v41
	v_sqrt_f32_e32 v44, v44
	v_sqrt_f32_e32 v45, v45
	s_waitcnt lgkmcnt(3)
	v_lshlrev_b32_e32 v102, 16, v102
	s_waitcnt lgkmcnt(2)
	v_lshlrev_b32_e32 v103, 16, v103
	v_pk_mul_f32 v[104:105], v[42:43], v[102:103]
	v_pk_mul_f32 v[40:41], v[40:41], v[44:45]
	s_waitcnt lgkmcnt(0)
; DI float bf2f(unsigned short b) { return __uint_as_float(((unsigned)b) << 16); }
; DI float ex2(float x) { return __builtin_amdgcn_exp2f(x); }
; DI float rcpf_(float x) { return __builtin_amdgcn_rcpf(x); }
; DI void lru_tile(const Params& p, unsigned char* shm, int c, int nb, const LruPar par) {
;     ...
;         for (int rt = 0; rt < 8; ++rt) {
;             float av[4], bv[4];
; #pragma unroll
;             for (int jp = 0; jp < 2; ++jp) {
;                 const f32x2 xr = {acc[0][rt][2 * jp], acc[0][rt][2 * jp + 1]}, xi = {acc[1][rt][2 * jp], acc[1][rt][2 * jp + 1]};
;                 f32x2 er = xr * nl2 + nbr2, ei = xi * nl2 + nbi2;
;                 er = (f32x2){ex2(er[0]), ex2(er[1])} + one2; ei = (f32x2){ex2(ei[0]), ex2(ei[1])} + one2;
;                 const f32x2 r = {rcpf_(er[0]), rcpf_(er[1])}, ig = {rcpf_(ei[0]), rcpf_(ei[1])};
;                 const f32x2 la = r * cd2;
;                 const f32x2 a = {ex2(la[0]), ex2(la[1])};
;                 const f32x2 om = one2 - a * a;
;                 const f32x2 sc = {__builtin_amdgcn_sqrtf(om[0]), __builtin_amdgcn_sqrtf(om[1])};
;                 const f32x2 u2 = {bf2f(UB[(rt * 16 + 4 * q + 2 * jp) * LDU + chl]), bf2f(UB[(rt * 16 + 4 * q + 2 * jp + 1) * LDU + chl])};
;                 const f32x2 b2 = sc * ig * u2;
;                 av[2 * jp] = a[0]; av[2 * jp + 1] = a[1]; bv[2 * jp] = b2[0]; bv[2 * jp + 1] = b2[1];
;             }
;             float h = 0.f, P = 1.f;
;             if (d == 0) {
; #pragma unroll
;                 for (int j = 0; j < 4; ++j) { h = fmaf(av[j], h, bv[j]); P *= av[j]; hl[rt][j] = h; pc[rt][j] = P; }
;             } else {
; #pragma unroll
;                 for (int j = 3; j >= 0; --j) { h = fmaf(av[j], h, bv[j]); P *= av[j]; hl[rt][j] = h; pc[rt][j] = P; }
;             }
;             AG[(rt * 4 + q) * 16 + col] = (f32x2){P, h};
;             __builtin_amdgcn_sched_barrier(0);
;         }
	v_lshlrev_b32_e32 v42, 16, v107
	v_lshlrev_b32_e32 v43, 16, v106
	v_pk_mul_f32 v[102:103], v[40:41], v[42:43]
	s_nop 0
	v_fma_f32 v102, 0, v100, v102
	v_fmac_f32_e32 v103, v101, v102
	v_mul_f32_e32 v101, v100, v101
	v_fma_f32 v106, v46, v103, v104
	v_mul_f32_e32 v108, v46, v101
	v_fmac_f32_e32 v105, v47, v106
	v_mul_f32_e32 v104, v47, v108
	ds_write_b64 v61, v[104:105] offset:1024
	v_pk_fma_f32 v[38:39], v[38:39], s[50:51], v[82:83] op_sel_hi:[1,0,0] neg_lo:[1,0,0] neg_hi:[1,0,0]
	v_pk_fma_f32 v[36:37], v[36:37], s[50:51], v[82:83] op_sel_hi:[1,0,0] neg_lo:[1,0,0] neg_hi:[1,0,0]
	v_exp_f32_e32 v38, v38
	v_exp_f32_e32 v39, v39
	v_exp_f32_e32 v36, v36
	v_exp_f32_e32 v37, v37
	v_pk_fma_f32 v[34:35], v[34:35], s[50:51], v[86:87] op_sel_hi:[1,0,0] neg_lo:[1,0,0] neg_hi:[1,0,0]
	v_pk_add_f32 v[38:39], v[38:39], 1.0 op_sel_hi:[1,0]
	v_exp_f32_e32 v34, v34
	v_rcp_f32_e32 v38, v38
	v_rcp_f32_e32 v39, v39
	v_pk_add_f32 v[36:37], v[36:37], 1.0 op_sel_hi:[1,0]
	v_exp_f32_e32 v35, v35
	v_rcp_f32_e32 v36, v36
	v_pk_mul_f32 v[38:39], v[92:93], v[38:39] op_sel_hi:[0,1]
	v_exp_f32_e32 v38, v38
	v_exp_f32_e32 v39, v39
	v_rcp_f32_e32 v37, v37
	v_pk_add_f32 v[34:35], v[34:35], 1.0 op_sel_hi:[1,0]
	v_pk_fma_f32 v[32:33], v[32:33], s[50:51], v[86:87] op_sel_hi:[1,0,0] neg_lo:[1,0,0] neg_hi:[1,0,0]
	v_pk_fma_f32 v[40:41], v[38:39], v[38:39], 1.0 op_sel_hi:[1,1,0] neg_lo:[1,0,0] neg_hi:[1,0,0]
	v_rcp_f32_e32 v34, v34
	v_rcp_f32_e32 v35, v35
	v_sqrt_f32_e32 v40, v40
	v_sqrt_f32_e32 v41, v41
	v_pk_mul_f32 v[36:37], v[92:93], v[36:37] op_sel_hi:[0,1]
	v_exp_f32_e32 v110, v36
	v_exp_f32_e32 v32, v32
	v_exp_f32_e32 v33, v33
	v_exp_f32_e32 v111, v37
	v_pk_mul_f32 v[34:35], v[34:35], v[40:41]
	ds_read_u16 v40, v68 offset:13600
	ds_read_u16 v41, v97 offset:13872
	v_pk_add_f32 v[32:33], v[32:33], 1.0 op_sel_hi:[1,0]
	v_pk_fma_f32 v[36:37], v[110:111], v[110:111], 1.0 op_sel_hi:[1,1,0] neg_lo:[1,0,0] neg_hi:[1,0,0]
	ds_read_u16 v42, v97 offset:13328
	ds_read_u16 v43, v68 offset:13056
	v_rcp_f32_e32 v32, v32
	v_rcp_f32_e32 v33, v33
	v_sqrt_f32_e32 v36, v36
	v_sqrt_f32_e32 v37, v37
	s_waitcnt lgkmcnt(3)
	v_lshlrev_b32_e32 v40, 16, v40
	s_waitcnt lgkmcnt(2)
	v_lshlrev_b32_e32 v41, 16, v41
	v_pk_mul_f32 v[114:115], v[34:35], v[40:41]
	v_pk_mul_f32 v[32:33], v[32:33], v[36:37]
	s_waitcnt lgkmcnt(0)
	v_lshlrev_b32_e32 v34, 16, v43
	v_lshlrev_b32_e32 v35, 16, v42
	v_pk_mul_f32 v[112:113], v[32:33], v[34:35]
	s_nop 0
	v_fma_f32 v112, 0, v110, v112
	v_fmac_f32_e32 v113, v111, v112
	v_mul_f32_e32 v111, v110, v111
	v_fma_f32 v116, v38, v113, v114
	v_mul_f32_e32 v118, v38, v111
	v_fmac_f32_e32 v115, v39, v116
	v_mul_f32_e32 v114, v39, v118
	ds_write_b64 v61, v[114:115] offset:1536
	v_pk_fma_f32 v[30:31], v[30:31], s[50:51], v[82:83] op_sel_hi:[1,0,0] neg_lo:[1,0,0] neg_hi:[1,0,0]
	v_pk_fma_f32 v[28:29], v[28:29], s[50:51], v[82:83] op_sel_hi:[1,0,0] neg_lo:[1,0,0] neg_hi:[1,0,0]
	v_exp_f32_e32 v30, v30
	v_exp_f32_e32 v31, v31
	v_exp_f32_e32 v28, v28
	v_exp_f32_e32 v29, v29
	v_pk_fma_f32 v[26:27], v[26:27], s[50:51], v[86:87] op_sel_hi:[1,0,0] neg_lo:[1,0,0] neg_hi:[1,0,0]
	v_pk_add_f32 v[30:31], v[30:31], 1.0 op_sel_hi:[1,0]
	v_exp_f32_e32 v26, v26
	v_rcp_f32_e32 v30, v30
	v_rcp_f32_e32 v31, v31
	v_pk_add_f32 v[28:29], v[28:29], 1.0 op_sel_hi:[1,0]
	v_exp_f32_e32 v27, v27
	v_rcp_f32_e32 v28, v28
	v_pk_mul_f32 v[30:31], v[92:93], v[30:31] op_sel_hi:[0,1]
	v_exp_f32_e32 v30, v30
	v_exp_f32_e32 v31, v31
	v_rcp_f32_e32 v29, v29
	v_pk_add_f32 v[26:27], v[26:27], 1.0 op_sel_hi:[1,0]
	v_pk_fma_f32 v[24:25], v[24:25], s[50:51], v[86:87] op_sel_hi:[1,0,0] neg_lo:[1,0,0] neg_hi:[1,0,0]
	v_pk_fma_f32 v[32:33], v[30:31], v[30:31], 1.0 op_sel_hi:[1,1,0] neg_lo:[1,0,0] neg_hi:[1,0,0]
	v_rcp_f32_e32 v26, v26
	v_rcp_f32_e32 v27, v27
	v_sqrt_f32_e32 v32, v32
	v_sqrt_f32_e32 v33, v33
	v_pk_mul_f32 v[28:29], v[92:93], v[28:29] op_sel_hi:[0,1]
	v_exp_f32_e32 v120, v28
	v_exp_f32_e32 v24, v24
	v_exp_f32_e32 v25, v25
	v_exp_f32_e32 v121, v29
	v_pk_mul_f32 v[26:27], v[26:27], v[32:33]
	ds_read_u16 v32, v68 offset:17952
	ds_read_u16 v33, v97 offset:18224
	v_pk_add_f32 v[24:25], v[24:25], 1.0 op_sel_hi:[1,0]
	v_pk_fma_f32 v[28:29], v[120:121], v[120:121], 1.0 op_sel_hi:[1,1,0] neg_lo:[1,0,0] neg_hi:[1,0,0]
	ds_read_u16 v34, v97 offset:17680
	ds_read_u16 v35, v68 offset:17408
	v_rcp_f32_e32 v24, v24
	v_rcp_f32_e32 v25, v25
	v_sqrt_f32_e32 v28, v28
	v_sqrt_f32_e32 v29, v29
	s_waitcnt lgkmcnt(3)
	v_lshlrev_b32_e32 v32, 16, v32
	s_waitcnt lgkmcnt(2)
	v_lshlrev_b32_e32 v33, 16, v33
	v_pk_mul_f32 v[124:125], v[26:27], v[32:33]
	v_pk_mul_f32 v[24:25], v[24:25], v[28:29]
	s_waitcnt lgkmcnt(0)
; DI float bf2f(unsigned short b) { return __uint_as_float(((unsigned)b) << 16); }
; DI float ex2(float x) { return __builtin_amdgcn_exp2f(x); }
; DI float rcpf_(float x) { return __builtin_amdgcn_rcpf(x); }
; DI void lru_tile(const Params& p, unsigned char* shm, int c, int nb, const LruPar par) {
;     ...
;         for (int rt = 0; rt < 8; ++rt) {
;             float av[4], bv[4];
; #pragma unroll
;             for (int jp = 0; jp < 2; ++jp) {
;                 const f32x2 xr = {acc[0][rt][2 * jp], acc[0][rt][2 * jp + 1]}, xi = {acc[1][rt][2 * jp], acc[1][rt][2 * jp + 1]};
;                 f32x2 er = xr * nl2 + nbr2, ei = xi * nl2 + nbi2;
;                 er = (f32x2){ex2(er[0]), ex2(er[1])} + one2; ei = (f32x2){ex2(ei[0]), ex2(ei[1])} + one2;
;                 const f32x2 r = {rcpf_(er[0]), rcpf_(er[1])}, ig = {rcpf_(ei[0]), rcpf_(ei[1])};
;                 const f32x2 la = r * cd2;
;                 const f32x2 a = {ex2(la[0]), ex2(la[1])};
;                 const f32x2 om = one2 - a * a;
;                 const f32x2 sc = {__builtin_amdgcn_sqrtf(om[0]), __builtin_amdgcn_sqrtf(om[1])};
;                 const f32x2 u2 = {bf2f(UB[(rt * 16 + 4 * q + 2 * jp) * LDU + chl]), bf2f(UB[(rt * 16 + 4 * q + 2 * jp + 1) * LDU + chl])};
;                 const f32x2 b2 = sc * ig * u2;
;                 av[2 * jp] = a[0]; av[2 * jp + 1] = a[1]; bv[2 * jp] = b2[0]; bv[2 * jp + 1] = b2[1];
;             }
;             float h = 0.f, P = 1.f;
;             if (d == 0) {
; #pragma unroll
;                 for (int j = 0; j < 4; ++j) { h = fmaf(av[j], h, bv[j]); P *= av[j]; hl[rt][j] = h; pc[rt][j] = P; }
;             } else {
; #pragma unroll
;                 for (int j = 3; j >= 0; --j) { h = fmaf(av[j], h, bv[j]); P *= av[j]; hl[rt][j] = h; pc[rt][j] = P; }
;             }
;             AG[(rt * 4 + q) * 16 + col] = (f32x2){P, h};
;             __builtin_amdgcn_sched_barrier(0);
;         }
	v_lshlrev_b32_e32 v26, 16, v35
	v_lshlrev_b32_e32 v27, 16, v34
	v_pk_mul_f32 v[122:123], v[24:25], v[26:27]
	s_nop 0
	v_fma_f32 v122, 0, v120, v122
	v_fmac_f32_e32 v123, v121, v122
	v_mul_f32_e32 v121, v120, v121
	v_fma_f32 v126, v30, v123, v124
	v_mul_f32_e32 v128, v30, v121
	v_fmac_f32_e32 v125, v31, v126
	v_mul_f32_e32 v124, v31, v128
	ds_write_b64 v61, v[124:125] offset:2048
	v_pk_fma_f32 v[22:23], v[22:23], s[50:51], v[82:83] op_sel_hi:[1,0,0] neg_lo:[1,0,0] neg_hi:[1,0,0]
	v_pk_fma_f32 v[20:21], v[20:21], s[50:51], v[82:83] op_sel_hi:[1,0,0] neg_lo:[1,0,0] neg_hi:[1,0,0]
	v_exp_f32_e32 v22, v22
	v_exp_f32_e32 v23, v23
	v_exp_f32_e32 v20, v20
	v_exp_f32_e32 v21, v21
	v_pk_fma_f32 v[18:19], v[18:19], s[50:51], v[86:87] op_sel_hi:[1,0,0] neg_lo:[1,0,0] neg_hi:[1,0,0]
	v_pk_add_f32 v[22:23], v[22:23], 1.0 op_sel_hi:[1,0]
	v_exp_f32_e32 v18, v18
	v_rcp_f32_e32 v22, v22
	v_rcp_f32_e32 v23, v23
	v_pk_add_f32 v[20:21], v[20:21], 1.0 op_sel_hi:[1,0]
	v_exp_f32_e32 v19, v19
	v_rcp_f32_e32 v20, v20
	v_pk_mul_f32 v[22:23], v[92:93], v[22:23] op_sel_hi:[0,1]
	v_exp_f32_e32 v22, v22
	v_exp_f32_e32 v23, v23
	v_rcp_f32_e32 v21, v21
	v_pk_add_f32 v[18:19], v[18:19], 1.0 op_sel_hi:[1,0]
	v_pk_fma_f32 v[16:17], v[16:17], s[50:51], v[86:87] op_sel_hi:[1,0,0] neg_lo:[1,0,0] neg_hi:[1,0,0]
	v_pk_fma_f32 v[24:25], v[22:23], v[22:23], 1.0 op_sel_hi:[1,1,0] neg_lo:[1,0,0] neg_hi:[1,0,0]
	v_rcp_f32_e32 v18, v18
	v_rcp_f32_e32 v19, v19
	v_sqrt_f32_e32 v24, v24
	v_sqrt_f32_e32 v25, v25
	v_pk_mul_f32 v[20:21], v[92:93], v[20:21] op_sel_hi:[0,1]
	v_exp_f32_e32 v130, v20
	v_exp_f32_e32 v16, v16
	v_exp_f32_e32 v17, v17
	v_exp_f32_e32 v131, v21
	v_pk_mul_f32 v[18:19], v[18:19], v[24:25]
	ds_read_u16 v24, v68 offset:22304
	ds_read_u16 v25, v97 offset:22576
	v_pk_add_f32 v[16:17], v[16:17], 1.0 op_sel_hi:[1,0]
	v_pk_fma_f32 v[20:21], v[130:131], v[130:131], 1.0 op_sel_hi:[1,1,0] neg_lo:[1,0,0] neg_hi:[1,0,0]
	ds_read_u16 v26, v97 offset:22032
	ds_read_u16 v27, v68 offset:21760
	v_rcp_f32_e32 v16, v16
	v_rcp_f32_e32 v17, v17
	v_sqrt_f32_e32 v20, v20
	v_sqrt_f32_e32 v21, v21
	s_waitcnt lgkmcnt(3)
	v_lshlrev_b32_e32 v24, 16, v24
	s_waitcnt lgkmcnt(2)
	v_lshlrev_b32_e32 v25, 16, v25
	v_pk_mul_f32 v[134:135], v[18:19], v[24:25]
	v_pk_mul_f32 v[16:17], v[16:17], v[20:21]
	s_waitcnt lgkmcnt(0)
	v_lshlrev_b32_e32 v18, 16, v27
	v_lshlrev_b32_e32 v19, 16, v26
	v_pk_mul_f32 v[132:133], v[16:17], v[18:19]
	s_nop 0
	v_fma_f32 v132, 0, v130, v132
	v_fmac_f32_e32 v133, v131, v132
	v_mul_f32_e32 v131, v130, v131
	v_fma_f32 v136, v22, v133, v134
	v_mul_f32_e32 v138, v22, v131
	v_fmac_f32_e32 v135, v23, v136
	v_mul_f32_e32 v134, v23, v138
	ds_write_b64 v61, v[134:135] offset:2560
	v_pk_fma_f32 v[14:15], v[14:15], s[50:51], v[82:83] op_sel_hi:[1,0,0] neg_lo:[1,0,0] neg_hi:[1,0,0]
	v_pk_fma_f32 v[12:13], v[12:13], s[50:51], v[82:83] op_sel_hi:[1,0,0] neg_lo:[1,0,0] neg_hi:[1,0,0]
	v_exp_f32_e32 v14, v14
	v_exp_f32_e32 v15, v15
	v_exp_f32_e32 v12, v12
	v_exp_f32_e32 v13, v13
	v_pk_fma_f32 v[10:11], v[10:11], s[50:51], v[86:87] op_sel_hi:[1,0,0] neg_lo:[1,0,0] neg_hi:[1,0,0]
	v_pk_add_f32 v[14:15], v[14:15], 1.0 op_sel_hi:[1,0]
	v_exp_f32_e32 v10, v10
	v_rcp_f32_e32 v14, v14
	v_rcp_f32_e32 v15, v15
	v_pk_add_f32 v[12:13], v[12:13], 1.0 op_sel_hi:[1,0]
	v_exp_f32_e32 v11, v11
	v_rcp_f32_e32 v12, v12
	v_pk_mul_f32 v[14:15], v[92:93], v[14:15] op_sel_hi:[0,1]
	v_exp_f32_e32 v14, v14
	v_exp_f32_e32 v15, v15
	v_rcp_f32_e32 v13, v13
	v_pk_add_f32 v[10:11], v[10:11], 1.0 op_sel_hi:[1,0]
	v_pk_fma_f32 v[8:9], v[8:9], s[50:51], v[86:87] op_sel_hi:[1,0,0] neg_lo:[1,0,0] neg_hi:[1,0,0]
	v_pk_fma_f32 v[16:17], v[14:15], v[14:15], 1.0 op_sel_hi:[1,1,0] neg_lo:[1,0,0] neg_hi:[1,0,0]
	v_rcp_f32_e32 v10, v10
	v_rcp_f32_e32 v11, v11
	v_sqrt_f32_e32 v16, v16
	v_sqrt_f32_e32 v17, v17
	v_pk_mul_f32 v[12:13], v[92:93], v[12:13] op_sel_hi:[0,1]
	v_exp_f32_e32 v140, v12
	v_exp_f32_e32 v8, v8
	v_exp_f32_e32 v9, v9
	v_exp_f32_e32 v141, v13
	v_pk_mul_f32 v[10:11], v[10:11], v[16:17]
	ds_read_u16 v16, v68 offset:26656
	ds_read_u16 v17, v97 offset:26928
	v_pk_add_f32 v[8:9], v[8:9], 1.0 op_sel_hi:[1,0]
	v_pk_fma_f32 v[12:13], v[140:141], v[140:141], 1.0 op_sel_hi:[1,1,0] neg_lo:[1,0,0] neg_hi:[1,0,0]
	ds_read_u16 v18, v97 offset:26384
	ds_read_u16 v19, v68 offset:26112
	v_rcp_f32_e32 v8, v8
	v_rcp_f32_e32 v9, v9
	v_sqrt_f32_e32 v12, v12
	v_sqrt_f32_e32 v13, v13
	s_waitcnt lgkmcnt(3)
	v_lshlrev_b32_e32 v16, 16, v16
	s_waitcnt lgkmcnt(2)
	v_lshlrev_b32_e32 v17, 16, v17
	v_pk_mul_f32 v[144:145], v[10:11], v[16:17]
	v_pk_mul_f32 v[8:9], v[8:9], v[12:13]
	s_waitcnt lgkmcnt(0)
	v_lshlrev_b32_e32 v10, 16, v19
	v_lshlrev_b32_e32 v11, 16, v18
	v_pk_mul_f32 v[142:143], v[8:9], v[10:11]
	s_nop 0
	v_fma_f32 v142, 0, v140, v142
	v_fmac_f32_e32 v143, v141, v142
	v_mul_f32_e32 v141, v140, v141
	v_fma_f32 v146, v14, v143, v144
	v_mul_f32_e32 v148, v14, v141
	v_fmac_f32_e32 v145, v15, v146
	v_mul_f32_e32 v144, v15, v148
	ds_write_b64 v61, v[144:145] offset:3072
	v_pk_fma_f32 v[6:7], v[6:7], s[50:51], v[82:83] op_sel_hi:[1,0,0] neg_lo:[1,0,0] neg_hi:[1,0,0]
	v_pk_fma_f32 v[4:5], v[4:5], s[50:51], v[82:83] op_sel_hi:[1,0,0] neg_lo:[1,0,0] neg_hi:[1,0,0]
	v_exp_f32_e32 v6, v6
	v_exp_f32_e32 v7, v7
	v_exp_f32_e32 v4, v4
	v_exp_f32_e32 v5, v5
	v_pk_fma_f32 v[2:3], v[2:3], s[50:51], v[86:87] op_sel_hi:[1,0,0] neg_lo:[1,0,0] neg_hi:[1,0,0]
	v_pk_add_f32 v[6:7], v[6:7], 1.0 op_sel_hi:[1,0]
	v_exp_f32_e32 v2, v2
	v_rcp_f32_e32 v6, v6
	v_rcp_f32_e32 v7, v7
	v_pk_add_f32 v[4:5], v[4:5], 1.0 op_sel_hi:[1,0]
	v_exp_f32_e32 v3, v3
	v_rcp_f32_e32 v4, v4
	v_pk_mul_f32 v[6:7], v[92:93], v[6:7] op_sel_hi:[0,1]
	v_exp_f32_e32 v6, v6
	v_exp_f32_e32 v7, v7
	v_rcp_f32_e32 v5, v5
	v_pk_add_f32 v[2:3], v[2:3], 1.0 op_sel_hi:[1,0]
	v_pk_fma_f32 v[0:1], v[0:1], s[50:51], v[86:87] op_sel_hi:[1,0,0] neg_lo:[1,0,0] neg_hi:[1,0,0]
	v_pk_fma_f32 v[8:9], v[6:7], v[6:7], 1.0 op_sel_hi:[1,1,0] neg_lo:[1,0,0] neg_hi:[1,0,0]
	v_rcp_f32_e32 v2, v2
	v_rcp_f32_e32 v3, v3
	v_sqrt_f32_e32 v8, v8
	v_sqrt_f32_e32 v9, v9
	v_pk_mul_f32 v[4:5], v[92:93], v[4:5] op_sel_hi:[0,1]
	v_exp_f32_e32 v150, v4
	v_exp_f32_e32 v0, v0
	v_exp_f32_e32 v1, v1
	v_exp_f32_e32 v151, v5
	v_pk_mul_f32 v[2:3], v[2:3], v[8:9]
	ds_read_u16 v8, v68 offset:31008
	ds_read_u16 v9, v97 offset:31280
	v_pk_add_f32 v[0:1], v[0:1], 1.0 op_sel_hi:[1,0]
	v_pk_fma_f32 v[4:5], v[150:151], v[150:151], 1.0 op_sel_hi:[1,1,0] neg_lo:[1,0,0] neg_hi:[1,0,0]
	ds_read_u16 v10, v97 offset:30736
	ds_read_u16 v11, v68 offset:30464
	v_rcp_f32_e32 v0, v0
	v_rcp_f32_e32 v1, v1
	v_sqrt_f32_e32 v4, v4
	v_sqrt_f32_e32 v5, v5
	s_waitcnt lgkmcnt(3)
; DI void lru_tile(const Params& p, unsigned char* shm, int c, int nb, const LruPar par) {
;     ...
;         asm volatile("s_waitcnt lgkmcnt(0)" ::: "memory");
;         float carry[8], pref[8]; float cin = 0.f, pa = 1.f;
; #pragma unroll
;         for (int gi = 0; gi < 32; ++gi) {
;             const int G = d == 0 ? gi : 31 - gi; const int rt = G >> 2, qq = G & 3;
;             const f32x2 ah = AG[G * 16 + col];
;             if (qq == q) { carry[rt] = cin; pref[rt] = pa; }
;             cin = fmaf(ah[0], cin, ah[1]); pa *= ah[0];
;         }
;         if (q == 0) AGG[((size_t)d * 128 + c) * 2048 + chg] = (f32x2){pa, cin};
	v_lshlrev_b32_e32 v8, 16, v8
	s_waitcnt lgkmcnt(2)
	v_lshlrev_b32_e32 v9, 16, v9
	v_pk_mul_f32 v[154:155], v[2:3], v[8:9]
	v_pk_mul_f32 v[0:1], v[0:1], v[4:5]
	s_waitcnt lgkmcnt(0)
	v_lshlrev_b32_e32 v2, 16, v11
	v_lshlrev_b32_e32 v3, 16, v10
	v_pk_mul_f32 v[152:153], v[0:1], v[2:3]
	s_nop 0
	v_fma_f32 v152, 0, v150, v152
	v_fmac_f32_e32 v153, v151, v152
	v_mul_f32_e32 v151, v150, v151
	v_fma_f32 v156, v6, v153, v154
	v_mul_f32_e32 v158, v6, v151
	v_fmac_f32_e32 v155, v7, v156
	v_mul_f32_e32 v154, v7, v158
	ds_write_b64 v61, v[154:155] offset:3584
	s_waitcnt lgkmcnt(0)
	ds_read2_b64 v[0:3], v59 offset1:16
	v_cndmask_b32_e64 v4, v180, 1.0, s[10:11]
	v_cmp_eq_u32_e64 s[4:5], 1, v99
	v_cmp_eq_u32_e64 s[6:7], 2, v99
	v_cmp_eq_u32_e64 s[8:9], 3, v99
	s_waitcnt lgkmcnt(0)
	v_cndmask_b32_e64 v8, v4, v0, s[4:5]
	ds_read2_b64 v[4:7], v59 offset0:32 offset1:48
	v_fma_f32 v119, 0, v0, v1
	v_cndmask_b32_e64 v9, 1.0, v0, s[4:5]
	v_fma_f32 v127, v2, v119, v3
	v_pk_mul_f32 v[0:1], v[0:1], v[2:3]
	s_waitcnt lgkmcnt(0)
	v_fma_f32 v129, v4, v127, v5
	v_cndmask_b32_e64 v2, v8, v0, s[6:7]
	v_pk_mul_f32 v[4:5], v[0:1], v[4:5]
	v_cndmask_b32_e64 v8, v9, v0, s[6:7]
	v_cndmask_b32_e64 v178, v2, v4, s[8:9]
	ds_read2_b64 v[0:3], v59 offset0:64 offset1:80
	v_cndmask_b32_e64 v181, v8, v4, s[8:9]
	v_fma_f32 v137, v6, v129, v7
	v_pk_mul_f32 v[4:5], v[4:5], v[6:7]
	s_waitcnt lgkmcnt(0)
	v_fma_f32 v139, v0, v137, v1
	v_cndmask_b32_e64 v8, v162, v4, s[10:11]
	v_pk_mul_f32 v[0:1], v[4:5], v[0:1]
	ds_read2_b64 v[4:7], v59 offset0:96 offset1:112
	v_cndmask_b32_e64 v8, v8, v0, s[4:5]
	v_fma_f32 v147, v2, v139, v3
	v_pk_mul_f32 v[0:1], v[0:1], v[2:3]
	ds_read_b64 v[162:163], v59 offset:3840
	v_cndmask_b32_e64 v8, v8, v0, s[6:7]
	s_waitcnt lgkmcnt(1)
	v_fma_f32 v149, v4, v147, v5
	v_pk_mul_f32 v[4:5], v[0:1], v[4:5]
	ds_read2_b64 v[0:3], v59 offset0:128 offset1:144
	v_cndmask_b32_e64 v99, v8, v4, s[8:9]
	v_fma_f32 v157, v6, v149, v7
	v_pk_mul_f32 v[4:5], v[4:5], v[6:7]
	s_waitcnt lgkmcnt(0)
	v_fma_f32 v159, v0, v157, v1
	v_cndmask_b32_e64 v8, v91, v4, s[10:11]
	v_pk_mul_f32 v[0:1], v[4:5], v[0:1]
	ds_read2_b64 v[4:7], v59 offset0:160 offset1:176
	v_cndmask_b32_e64 v8, v8, v0, s[4:5]
	v_fma_f32 v183, v2, v159, v3
	v_pk_mul_f32 v[0:1], v[0:1], v[2:3]
	s_waitcnt lgkmcnt(0)
	v_fma_f32 v184, v4, v183, v5
	v_cndmask_b32_e64 v8, v8, v0, s[6:7]
	v_pk_mul_f32 v[4:5], v[0:1], v[4:5]
	ds_read2_b64 v[0:3], v59 offset0:192 offset1:208
	v_cndmask_b32_e64 v107, v8, v4, s[8:9]
	v_fma_f32 v185, v6, v184, v7
	v_pk_mul_f32 v[4:5], v[4:5], v[6:7]
	s_waitcnt lgkmcnt(0)
	v_fma_f32 v186, v0, v185, v1
	v_cndmask_b32_e64 v8, v89, v4, s[10:11]
	v_pk_mul_f32 v[0:1], v[4:5], v[0:1]
	ds_read2_b64 v[4:7], v59 offset0:224 offset1:240
	v_cndmask_b32_e64 v8, v8, v0, s[4:5]
	v_fma_f32 v187, v2, v186, v3
	v_pk_mul_f32 v[0:1], v[0:1], v[2:3]
	v_add_u32_e32 v89, 0x800, v59
	v_cndmask_b32_e64 v8, v8, v0, s[6:7]
	s_waitcnt lgkmcnt(0)
	v_fma_f32 v188, v4, v187, v5
	v_pk_mul_f32 v[4:5], v[0:1], v[4:5]
	ds_read2_b64 v[0:3], v89 offset1:16
	v_cndmask_b32_e64 v109, v8, v4, s[8:9]
	v_fma_f32 v189, v6, v188, v7
	v_pk_mul_f32 v[4:5], v[4:5], v[6:7]
	s_waitcnt lgkmcnt(0)
	v_fma_f32 v190, v0, v189, v1
	v_cndmask_b32_e64 v8, v85, v4, s[10:11]
	v_pk_mul_f32 v[0:1], v[4:5], v[0:1]
	ds_read2_b64 v[4:7], v89 offset0:32 offset1:48
	v_cndmask_b32_e64 v8, v8, v0, s[4:5]
	v_fma_f32 v192, v2, v190, v3
	v_pk_mul_f32 v[0:1], v[0:1], v[2:3]
	s_waitcnt lgkmcnt(0)
	v_fma_f32 v193, v4, v192, v5
	v_cndmask_b32_e64 v8, v8, v0, s[6:7]
	v_pk_mul_f32 v[4:5], v[0:1], v[4:5]
	ds_read2_b64 v[0:3], v89 offset0:64 offset1:80
	v_cndmask_b32_e64 v117, v8, v4, s[8:9]
	v_fma_f32 v194, v6, v193, v7
	v_pk_mul_f32 v[4:5], v[4:5], v[6:7]
	s_waitcnt lgkmcnt(0)
	v_fma_f32 v195, v0, v194, v1
	v_cndmask_b32_e64 v8, v81, v4, s[10:11]
	v_pk_mul_f32 v[0:1], v[4:5], v[0:1]
	ds_read2_b64 v[4:7], v89 offset0:96 offset1:112
	v_cndmask_b32_e64 v8, v8, v0, s[4:5]
	v_fma_f32 v196, v2, v195, v3
	v_pk_mul_f32 v[0:1], v[0:1], v[2:3]
	s_waitcnt lgkmcnt(0)
	v_fma_f32 v197, v4, v196, v5
	v_cndmask_b32_e64 v8, v8, v0, s[6:7]
	v_pk_mul_f32 v[4:5], v[0:1], v[4:5]
	ds_read2_b64 v[0:3], v89 offset0:128 offset1:144
	v_cndmask_b32_e64 v182, v8, v4, s[8:9]
	v_fma_f32 v198, v6, v197, v7
	v_pk_mul_f32 v[4:5], v[4:5], v[6:7]
	s_waitcnt lgkmcnt(0)
	v_fma_f32 v200, v0, v198, v1
	v_cndmask_b32_e64 v8, v79, v4, s[10:11]
	v_pk_mul_f32 v[0:1], v[4:5], v[0:1]
	ds_read2_b64 v[4:7], v89 offset0:160 offset1:176
	v_cndmask_b32_e64 v8, v8, v0, s[4:5]
	v_fma_f32 v201, v2, v200, v3
	v_pk_mul_f32 v[0:1], v[0:1], v[2:3]
	s_waitcnt lgkmcnt(0)
	v_fma_f32 v204, v4, v201, v5
	v_cndmask_b32_e64 v8, v8, v0, s[6:7]
	v_pk_mul_f32 v[4:5], v[0:1], v[4:5]
	ds_read2_b64 v[0:3], v89 offset0:192 offset1:208
	v_cndmask_b32_e64 v191, v8, v4, s[8:9]
	v_fma_f32 v205, v6, v204, v7
	v_pk_mul_f32 v[4:5], v[4:5], v[6:7]
	s_waitcnt lgkmcnt(0)
	v_fma_f32 v206, v0, v205, v1
	v_cndmask_b32_e64 v6, v77, v4, s[10:11]
	v_pk_mul_f32 v[0:1], v[4:5], v[0:1]
	v_fma_f32 v207, v2, v206, v3
	v_cndmask_b32_e64 v4, v6, v0, s[4:5]
	v_pk_mul_f32 v[0:1], v[0:1], v[2:3]
	s_nop 0
	v_cndmask_b32_e64 v77, v4, v0, s[6:7]
	v_pk_mul_f32 v[0:1], v[0:1], v[162:163]
	v_fmac_f32_e32 v163, v162, v207
	v_cndmask_b32_e64 v199, v77, v0, s[8:9]
	s_and_saveexec_b64 s[60:61], s[10:11]
	s_cbranch_execz .LBB0_230
	ds_read_b64 v[2:3], v59 offset:3968
	v_mov_b32_e32 v181, v178
	s_waitcnt lgkmcnt(0)
	v_pk_mul_f32 v[0:1], v[0:1], v[2:3]
	v_fmac_f32_e32 v3, v2, v163
	v_mov_b32_e32 v1, v3
	global_store_dwordx2 v[56:57], v[0:1], off
